# v20 + LRU item loops rebalanced: WGs with two static-GEMM units take 22 items, their partners 26
# speedup vs baseline: 1.0043x; 1.0043x over previous
; __device__ __forceinline__ u32x4 pack8(f32x4 v0, f32x4 v1) { u32x4 w; w.x = cvt_pk_bf16(v0[0], v0[1]); w.y = cvt_pk_bf16(v0[2], v0[3]); w.z = cvt_pk_bf16(v1[0], v1[1]); w.w = cvt_pk_bf16(v1[2], v1[3]); return w; }
; __device__ __forceinline__ void unpack8(u32x4 w, f32x4& v0, f32x4& v1) { v0 = (f32x4){bflo(w.x), bfhi(w.x), bflo(w.y), bfhi(w.y)}; v1 = (f32x4){bflo(w.z), bfhi(w.z), bflo(w.w), bfhi(w.w)}; }
; template <int PASS>
; __device__ void lru_items(const Params& p, unsigned char* shm, int l) {
;     ...
;                 float c = cin;
; #pragma unroll
;                 for (int q = 0; q < 3; ++q) if (q < seg) c = Pq[q * 128 + (tid & 127)] * c + Hq[q * 128 + (tid & 127)];
; #pragma unroll
;                 for (int s = 0; s < 16; ++s) { const int st = seg * 16 + s, t = d ? 63 - st : st; c = As[(d * 64 + t) * 64 + j] * c + Bs[(d * 64 + t) * 64 + j]; Bs[(d * 64 + t) * 64 + j] = c; }
;                 __syncthreads();
;                 const int t = tid >> 3, c8 = tid & 7;
;                 f32x4 g0, g1; unpack8(glv, g0, g1);
;                 const f32x4 f0 = *(const f32x4*)(Bs + t * 64 + c8 * 8), f1 = *(const f32x4*)(Bs + t * 64 + c8 * 8 + 4), r0 = *(const f32x4*)(Bs + (64 + t) * 64 + c8 * 8), r1 = *(const f32x4*)(Bs + (64 + t) * 64 + c8 * 8 + 4);
;                 *(u32x4*)(GL + go) = pack8((f0 + r0) * g0, (f1 + r1) * g1);
.LBB0_199:
	s_or_b64 exec, exec, s[0:1]
	ds_read_b32 v183, v51
	ds_read_b32 v200, v106
	ds_read_b32 v184, v107
	ds_read_b32 v201, v108
	ds_read_b32 v185, v109
	ds_read_b32 v202, v110
	ds_read_b32 v186, v111
	ds_read_b32 v203, v112
	ds_read_b32 v187, v113
	ds_read_b32 v204, v114
	ds_read_b32 v188, v115
	ds_read_b32 v205, v116
	ds_read_b32 v189, v117
	ds_read_b32 v206, v118
	ds_read_b32 v190, v119
	ds_read_b32 v207, v120
	ds_read_b32 v191, v121
	ds_read_b32 v208, v122
	ds_read_b32 v192, v123
	ds_read_b32 v209, v124
	ds_read_b32 v193, v125
	ds_read_b32 v210, v126
	ds_read_b32 v194, v127
	ds_read_b32 v211, v128
	ds_read_b32 v196, v129
	ds_read_b32 v212, v130
	ds_read_b32 v197, v131
	ds_read_b32 v213, v132
	ds_read_b32 v198, v133
	ds_read_b32 v214, v134
	ds_read_b32 v199, v135
	ds_read_b32 v215, v136
	s_waitcnt vmcnt(0)
	v_lshlrev_b32_e32 v172, 16, v10
	v_and_b32_e32 v173, 0xffff0000, v10
	v_lshlrev_b32_e32 v174, 16, v11
	v_and_b32_e32 v175, 0xffff0000, v11
	v_lshlrev_b32_e32 v176, 16, v12
	v_and_b32_e32 v177, 0xffff0000, v12
	v_lshlrev_b32_e32 v178, 16, v13
	v_and_b32_e32 v179, 0xffff0000, v13
	s_waitcnt lgkmcnt(0)
	v_fmac_f32_e32 v200, v34, v183
	ds_write_b32 v106, v200
	v_fmac_f32_e32 v201, v200, v184
	ds_write_b32 v108, v201
	v_fmac_f32_e32 v202, v201, v185
	ds_write_b32 v110, v202
	v_fmac_f32_e32 v203, v202, v186
	ds_write_b32 v112, v203
	v_fmac_f32_e32 v204, v203, v187
	ds_write_b32 v114, v204
	v_fmac_f32_e32 v205, v204, v188
	ds_write_b32 v116, v205
	v_fmac_f32_e32 v206, v205, v189
	ds_write_b32 v118, v206
	v_fmac_f32_e32 v207, v206, v190
	ds_write_b32 v120, v207
	v_fmac_f32_e32 v208, v207, v191
	ds_write_b32 v122, v208
	v_fmac_f32_e32 v209, v208, v192
	ds_write_b32 v124, v209
	v_fmac_f32_e32 v210, v209, v193
	ds_write_b32 v126, v210
	v_fmac_f32_e32 v211, v210, v194
	ds_write_b32 v128, v211
	v_fmac_f32_e32 v212, v211, v196
	ds_write_b32 v130, v212
	v_fmac_f32_e32 v213, v212, v197
	ds_write_b32 v132, v213
	v_fmac_f32_e32 v214, v213, v198
	ds_write_b32 v134, v214
	v_fmac_f32_e32 v215, v214, v199
	ds_write_b32 v136, v215
	v_mov_b64_e32 v[34:35], v[24:25]
	v_mov_b64_e32 v[36:37], v[22:23]
	v_readlane_b32 s0, v253, 61
	s_and_b64 vcc, exec, s[46:47]
	s_mov_b32 s5, s4
	v_mov_b32_e32 v159, v151
	v_mov_b32_e32 v160, v154
	v_mov_b32_e32 v161, v153
	v_mov_b32_e32 v162, v152
	v_mov_b32_e32 v163, v150
	v_mov_b32_e32 v164, v157
	v_mov_b32_e32 v165, v158
	v_mov_b32_e32 v166, v40
	v_mov_b32_e32 v167, v41
	v_mov_b32_e32 v168, v155
	v_mov_b32_e32 v169, v156
	v_mov_b32_e32 v170, v38
	v_mov_b32_e32 v171, v39
	s_waitcnt lgkmcnt(0)
	s_barrier
	ds_read_b128 v[10:13], v50 offset:16384
	ds_read_b128 v[14:17], v50
	ds_read_b128 v[18:21], v50 offset:16
	ds_read_b128 v[22:25], v50 offset:16400
	s_waitcnt lgkmcnt(2)
	v_pk_add_f32 v[12:13], v[16:17], v[12:13]
	v_pk_add_f32 v[10:11], v[14:15], v[10:11]
	s_waitcnt lgkmcnt(0)
	v_pk_add_f32 v[14:15], v[20:21], v[24:25]
	v_pk_add_f32 v[16:17], v[18:19], v[22:23]
	v_pk_mul_f32 v[12:13], v[12:13], v[174:175]
	v_pk_mul_f32 v[10:11], v[10:11], v[172:173]
	v_pk_mul_f32 v[14:15], v[14:15], v[178:179]
	v_pk_mul_f32 v[16:17], v[16:17], v[176:177]
	v_cvt_pk_bf16_f32 v10, v10, v11
	v_cvt_pk_bf16_f32 v11, v12, v13
	v_cvt_pk_bf16_f32 v13, v14, v15
	s_nop 0
	v_cvt_pk_bf16_f32 v12, v16, v17
	global_store_dwordx4 v[32:33], v[10:13], off
	s_barrier
	s_cbranch_vccnz .LBB0_220

; __device__ __forceinline__ int lbid() { int b = blockIdx.x; asm volatile("" : "+s"(b)); return b; }
; template <int PASS>
; __device__ void lru_items(const Params& p, unsigned char* shm, int l) {
;     ...
;     int it = lbid();
;     if (it < total) LRU_LOAD(it);
;     for (; it < total; it += G_) {
;         const int ck = it >> 4, n = it & 15, t0 = ck * 64;
;         *(u32x4*)(xraw + (tid >> 3) * 64 + (tid & 7) * 8) = xr0;
;         if (tid < 24) *(u32x4*)(xraw + (64 + (tid >> 3)) * 64 + (tid & 7) * 8) = xr1;
;         if (n != n_loaded) {
;             n_loaded = n;
; #pragma unroll
;             for (int i = 0; i < 4; ++i) { const int e = tid + 512 * i, mtx = e >> 9, rem = e & 511, j = rem >> 3, c8 = rem & 7;
;                 *(u32x4*)(wt + (mtx * 64 + j) * 72 + c8 * 8) = *(const u32x4*)(LWT + ((size_t)(mtx * 16 + n) * 64 + j) * 64 + c8 * 8); }
;             { const int ch = n * 64 + (tid & 63); c0 = cw[ch]; c1 = cw[1024 + ch]; c2 = cw[2048 + ch]; c3 = cw[3072 + ch]; cb = cbias[ch]; }
; #pragma unroll
;             for (int jt = 0; jt < 4; ++jt) { const int pi = (l * 2 + (w >> 2)) * 1024 + n * 64 + jt * 16 + fr; gba[jt] = p.in[7][pi]; gbx[jt] = p.in[9][pi]; gsp[jt] = -8.0f * log1pf(__expf(-p.in[10][pi])); }
;         }
;         u32x4 glv = (u32x4){0u, 0u, 0u, 0u}; float cin = 0.f;
;         const size_t go = (size_t)(t0 + (tid >> 3)) * 1024 + n * 64 + (tid & 7) * 8;
;         const size_t so = (size_t)(ck * 2 + ((tid >> 6) & 1)) * 1024 + n * 64 + (tid & 63);
;         if (PASS == 1) { glv = *(const u32x4*)(GL + go); cin = CIN[so]; }
;         asm volatile("" ::: "memory");
;         __syncthreads();
;         if (it + G_ < total) LRU_LOAD(it + G_);
.LBB0_206:
	s_ashr_i32 s0, s2, 4
	v_lshl_add_u32 v10, s0, 6, v27
	v_ashrrev_i32_e32 v11, 31, v10
	v_lshl_or_b32 v12, s0, 1, v46
	v_readlane_b32 s0, v252, 13
	v_lshlrev_b64 v[10:11], 11, v[10:11]
	v_readlane_b32 s1, v252, 14
	v_ashrrev_i32_e32 v13, 31, v12
	v_lshlrev_b32_e32 v0, 1, v26
	v_lshl_add_u64 v[10:11], s[0:1], 0, v[10:11]
	v_lshl_add_u64 v[10:11], s[48:49], 1, v[10:11]
	v_lshl_add_u64 v[32:33], v[10:11], 0, v[0:1]
	v_lshlrev_b64 v[10:11], 12, v[12:13]
	v_lshl_add_u64 v[10:11], v[30:31], 0, v[10:11]
	v_lshl_add_u64 v[14:15], s[48:49], 2, v[10:11]
	global_load_dwordx4 v[10:13], v[32:33], off
	global_load_dword v34, v[14:15], off
	v_readlane_b32 s0, v251, 10
	v_readlane_b32 s1, v254, 20
	s_add_i32 s2, s2, s0
	s_cmpk_ge_i32 s2, 0x1880
	s_cselect_b32 s0, 0x280, 0
	s_sub_i32 s2, s2, s0
	s_lshl_b32 s3, s2, 2
	s_movk_i32 s0, 0x17ff
	s_cmpk_lt_i32 s1, 0x80
	s_cselect_b32 s0, 0x15ff, s0
	s_cmp_gt_i32 s2, s0
	s_cselect_b64 s[46:47], -1, 0
	s_and_b64 vcc, exec, s[46:47]
	s_waitcnt lgkmcnt(0)
	s_barrier
	v_readlane_b32 s1, v251, 11
	s_cbranch_vccnz .LBB0_214
	s_and_b32 s1, s3, 0xfffff800
	s_and_b32 s5, s2, 15
	s_and_b32 s0, s3, 0xffffffc0
	s_add_i32 s7, s1, 0x800
	s_cmpk_lt_i32 s0, 0x2000
	s_cselect_b32 s6, s1, 0x2000
	s_cselect_b32 s7, s7, 0x6000
	v_add_u32_e32 v14, s0, v42
	v_cmp_le_i32_e32 vcc, s6, v14
	v_cmp_gt_i32_e64 s[44:45], s7, v14
	s_and_b64 s[8:9], vcc, s[44:45]
	v_mov_b32_e32 v2, v1
	v_mov_b32_e32 v3, v1
	v_mov_b32_e32 v4, v1
	v_mov_b32_e32 v5, v1
	s_and_saveexec_b64 s[0:1], s[8:9]
	s_cbranch_execz .LBB0_209
	v_ashrrev_i32_e32 v15, 31, v14
	v_readlane_b32 s8, v252, 9
	v_lshlrev_b64 v[2:3], 11, v[14:15]
	v_readlane_b32 s9, v252, 10
	s_lshl_b32 s48, s5, 7
	s_nop 0
	v_lshl_add_u64 v[2:3], s[8:9], 0, v[2:3]
	v_lshl_add_u64 v[2:3], v[2:3], 0, s[48:49]
	v_lshl_add_u64 v[2:3], v[2:3], 0, v[0:1]
	global_load_dwordx4 v[2:5], v[2:3], off

; __device__ __forceinline__ u32x4 pack8(f32x4 v0, f32x4 v1) { u32x4 w; w.x = cvt_pk_bf16(v0[0], v0[1]); w.y = cvt_pk_bf16(v0[2], v0[3]); w.z = cvt_pk_bf16(v1[0], v1[1]); w.w = cvt_pk_bf16(v1[2], v1[3]); return w; }
; __device__ __forceinline__ void unpack8(u32x4 w, f32x4& v0, f32x4& v1) { v0 = (f32x4){bflo(w.x), bfhi(w.x), bflo(w.y), bfhi(w.y)}; v1 = (f32x4){bflo(w.z), bfhi(w.z), bflo(w.w), bfhi(w.w)}; }
; template <int PASS>
; __device__ void lru_items(const Params& p, unsigned char* shm, int l) {
;     ...
;             if (PASS == 0) {
;                 if (tid < 128) { float hh = Hq[tid], PP = Pq[tid];
; #pragma unroll
;                     for (int q = 1; q < 4; ++q) { const float pq = Pq[q * 128 + tid]; hh = pq * hh + Hq[q * 128 + tid]; PP *= pq; }
;                     SA[so] = PP; SH[so] = hh; }
;             } else {
;                 float c = cin;
; #pragma unroll
;                 for (int q = 0; q < 3; ++q) if (q < seg) c = Pq[q * 128 + (tid & 127)] * c + Hq[q * 128 + (tid & 127)];
; #pragma unroll
;                 for (int s = 0; s < 16; ++s) { const int st = seg * 16 + s, t = d ? 63 - st : st; c = As[(d * 64 + t) * 64 + j] * c + Bs[(d * 64 + t) * 64 + j]; Bs[(d * 64 + t) * 64 + j] = c; }
;                 __syncthreads();
;                 const int t = tid >> 3, c8 = tid & 7;
;                 f32x4 g0, g1; unpack8(glv, g0, g1);
;                 const f32x4 f0 = *(const f32x4*)(Bs + t * 64 + c8 * 8), f1 = *(const f32x4*)(Bs + t * 64 + c8 * 8 + 4), r0 = *(const f32x4*)(Bs + (64 + t) * 64 + c8 * 8), r1 = *(const f32x4*)(Bs + (64 + t) * 64 + c8 * 8 + 4);
;                 *(u32x4*)(GL + go) = pack8((f0 + r0) * g0, (f1 + r1) * g1);
;             }
;         }
;         __syncthreads();
.LBB0_295:
	s_or_b64 exec, exec, s[40:41]
	v_readlane_b32 s0, v253, 61
	s_andn2_b64 vcc, exec, s[54:55]
	s_mov_b32 s6, s4
	v_mov_b32_e32 v153, v149
	v_mov_b32_e32 v154, v152
	v_mov_b32_e32 v155, v151
	v_mov_b32_e32 v156, v150
	v_mov_b32_e32 v157, v148
	s_mov_b32 s2, s5
	v_mov_b64_e32 v[32:33], v[20:21]
	v_mov_b64_e32 v[34:35], v[18:19]
	v_mov_b32_e32 v158, v22
	v_mov_b32_e32 v159, v23
	v_mov_b32_e32 v160, v24
	v_mov_b32_e32 v161, v25
	v_mov_b32_e32 v162, v38
	v_mov_b32_e32 v163, v39
	v_mov_b32_e32 v164, v40
	v_mov_b32_e32 v165, v36
	s_barrier
	s_cbranch_vccz .LBB0_312

; __device__ __forceinline__ int lbid() { int b = blockIdx.x; asm volatile("" : "+s"(b)); return b; }
; template <int PASS>
; __device__ void lru_items(const Params& p, unsigned char* shm, int l) {
;     ...
;     int it = lbid();
;     if (it < total) LRU_LOAD(it);
;     for (; it < total; it += G_) {
;         const int ck = it >> 4, n = it & 15, t0 = ck * 64;
;         *(u32x4*)(xraw + (tid >> 3) * 64 + (tid & 7) * 8) = xr0;
;         if (tid < 24) *(u32x4*)(xraw + (64 + (tid >> 3)) * 64 + (tid & 7) * 8) = xr1;
;         if (n != n_loaded) {
;             n_loaded = n;
; #pragma unroll
;             for (int i = 0; i < 4; ++i) { const int e = tid + 512 * i, mtx = e >> 9, rem = e & 511, j = rem >> 3, c8 = rem & 7;
;                 *(u32x4*)(wt + (mtx * 64 + j) * 72 + c8 * 8) = *(const u32x4*)(LWT + ((size_t)(mtx * 16 + n) * 64 + j) * 64 + c8 * 8); }
;             { const int ch = n * 64 + (tid & 63); c0 = cw[ch]; c1 = cw[1024 + ch]; c2 = cw[2048 + ch]; c3 = cw[3072 + ch]; cb = cbias[ch]; }
; #pragma unroll
;             for (int jt = 0; jt < 4; ++jt) { const int pi = (l * 2 + (w >> 2)) * 1024 + n * 64 + jt * 16 + fr; gba[jt] = p.in[7][pi]; gbx[jt] = p.in[9][pi]; gsp[jt] = -8.0f * log1pf(__expf(-p.in[10][pi])); }
;         }
;         u32x4 glv = (u32x4){0u, 0u, 0u, 0u}; float cin = 0.f;
;         const size_t go = (size_t)(t0 + (tid >> 3)) * 1024 + n * 64 + (tid & 7) * 8;
;         const size_t so = (size_t)(ck * 2 + ((tid >> 6) & 1)) * 1024 + n * 64 + (tid & 63);
;         if (PASS == 1) { glv = *(const u32x4*)(GL + go); cin = CIN[so]; }
;         asm volatile("" ::: "memory");
;         __syncthreads();
;         if (it + G_ < total) LRU_LOAD(it + G_);
.LBB0_302:
	v_readlane_b32 s0, v251, 10
	v_readlane_b32 s1, v254, 20
	s_add_i32 s5, s2, s0
	s_cmpk_ge_i32 s5, 0x1880
	s_cselect_b32 s0, 0x280, 0
	s_sub_i32 s5, s5, s0
	s_lshl_b32 s3, s5, 2
	s_movk_i32 s0, 0x17ff
	s_cmpk_lt_i32 s1, 0x80
	s_cselect_b32 s0, 0x15ff, s0
	s_cmp_gt_i32 s5, s0
	s_cselect_b64 s[54:55], -1, 0
	s_and_b64 vcc, exec, s[54:55]
	s_waitcnt lgkmcnt(0)
	s_barrier
	v_readlane_b32 s1, v251, 11
	s_cbranch_vccnz .LBB0_310
	s_and_b32 s1, s3, 0xfffff800
	s_and_b32 s6, s5, 15
	s_and_b32 s0, s3, 0xffffffc0
	s_add_i32 s8, s1, 0x800
	s_cmpk_lt_i32 s0, 0x2000
	s_cselect_b32 s7, s1, 0x2000
	s_cselect_b32 s8, s8, 0x6000
	v_add_u32_e32 v10, s0, v27
	v_mov_b32_e32 v2, v1
	v_mov_b32_e32 v3, v1
	v_cmp_le_i32_e32 vcc, s7, v10
	v_cmp_gt_i32_e64 s[40:41], s8, v10
	v_mov_b32_e32 v0, v1
	v_mov_b64_e32 v[4:5], v[2:3]
	s_and_b64 s[18:19], vcc, s[40:41]
	v_mov_b64_e32 v[2:3], v[0:1]
	s_and_saveexec_b64 s[0:1], s[18:19]
	s_cbranch_execz .LBB0_305
	v_ashrrev_i32_e32 v11, 31, v10
	v_readlane_b32 s18, v252, 9
	v_lshlrev_b64 v[2:3], 11, v[10:11]
	v_readlane_b32 s19, v252, 10
	s_lshl_b32 s48, s6, 7
	v_lshlrev_b32_e32 v0, 1, v28
	v_lshl_add_u64 v[2:3], s[18:19], 0, v[2:3]
	v_lshl_add_u64 v[2:3], v[2:3], 0, s[48:49]
	v_lshl_add_u64 v[2:3], v[2:3], 0, v[0:1]
	global_load_dwordx4 v[2:5], v[2:3], off
